# M1 ret_kv: all eight K/V row loads requested at once (were issued one or two at a time between the zeta scaling steps)
# baseline (speedup 1.0000x reference)
; #define LAS __attribute__((address_space(3)))
; __device__ __forceinline__ unsigned pk2(float lo, float hi) { return pg8::cvt_pk_bf16(lo, hi); }
; __device__ __forceinline__ float ret_lg2(int h) { return log2f(1.0f - exp2f(-5.0f - (float)h)); }
; template <int NR, bool ZETA> __device__ __forceinline__ void ret_load_R(const bf16* Z, int r0, int c0, LAS unsigned char* dst, int tid, float lg2) {
; #pragma unroll
;     for (int it = 0; it < NR / 32; ++it) { const int ch = it * NTHR + tid, r = ch >> 4, c = ch & 15;
;         u32x4 v = *(const u32x4*)(Z + (size_t)(r0 + r) * IW + c0 + c * 8);
;         if (ZETA) { const float zs = __builtin_amdgcn_exp2f((float)(127 - r) * lg2); float f[8]; unpack8(v, f);
;             v.x = pk2(f[0] * zs, f[1] * zs); v.y = pk2(f[2] * zs, f[3] * zs); v.z = pk2(f[4] * zs, f[5] * zs); v.w = pk2(f[6] * zs, f[7] * zs); }
;         *(LAS u32x4*)(dst + (r * 136 + c * 8) * 2) = v; }
; __device__ __forceinline__ void ret_kv(const Args& a, int unit, LAS unsigned char* lds, int tid, int lane, int wave) {
;     const bf16* Z = (const bf16*)(a.ws + WS_HZ);
;     const int n = unit & 63, bh = unit >> 6, h = bh & 3, b = bh >> 2, r0 = b * SEQ + n * 128, fr = lane & 15, fq = lane >> 4;
;     const float lg2 = ret_lg2(h);
;     ret_load_R<128, true>(Z, r0, 768 + h * 128, lds + OFF_KS, tid, lg2);
;     ret_load_R<128, false>(Z, r0, 1280 + h * 128, lds + OFF_VT, tid, lg2);
.LBB0_1263:
	s_bfe_u32 s1, s4, 0x20006
	v_cvt_f32_ubyte0_e32 v0, s1
	v_sub_f32_e32 v0, 0xc0a00000, v0
	v_cmp_gt_f32_e32 vcc, s87, v0
	s_lshl_b32 s0, s4, 5
	s_lshl_b32 s5, s4, 7
	v_cndmask_b32_e32 v1, 0, v192, vcc
	v_add_f32_e32 v0, v0, v1
	s_and_b32 s0, s0, 0xffffe000
	s_and_b32 s5, s5, 0x1f80
	v_exp_f32_e32 v0, v0
	s_or_b32 s0, s0, s5
	s_and_b64 s[28:29], vcc, exec
	s_cselect_b32 s5, 0xffffffc0, 0
	v_ldexp_f32 v0, v0, s5
	v_sub_f32_e32 v1, 1.0, v0
	v_cmp_gt_f32_e32 vcc, s33, v1
	s_and_b64 s[28:29], vcc, exec
	s_cselect_b32 s5, 32, 0
	s_lshl_b32 s1, s1, 8
	v_lshlrev_b32_e32 v0, 3, v76
	s_add_u32 s28, s8, s1
	v_and_b32_e32 v0, 0x78, v0
	s_addc_u32 s29, s9, 0
	v_lshlrev_b32_e32 v144, 1, v0
	v_ashrrev_i32_e32 v16, 4, v76
	v_lshl_add_u64 v[10:11], s[28:29], 0, v[144:145]
	v_add_u32_e32 v2, s0, v16
	v_mad_i64_i32 v[12:13], s[28:29], v2, s84, v[10:11]
	v_mov_b32_e32 v230, 0x2c000
	v_mov_b32_e32 v231, 0
	v_lshl_add_u64 v[232:233], v[12:13], 0, v[230:231]
	v_lshl_add_u64 v[234:235], v[232:233], 0, v[230:231]
	v_lshl_add_u64 v[236:237], v[234:235], 0, v[230:231]
	global_load_dwordx4 v[198:201], v[12:13], off offset:1536
	global_load_dwordx4 v[202:205], v[232:233], off offset:1536
	global_load_dwordx4 v[206:209], v[234:235], off offset:1536
	global_load_dwordx4 v[210:213], v[236:237], off offset:1536
	global_load_dwordx4 v[214:217], v[12:13], off offset:2560
	global_load_dwordx4 v[218:221], v[232:233], off offset:2560
	global_load_dwordx4 v[222:225], v[234:235], off offset:2560
	global_load_dwordx4 v[226:229], v[236:237], off offset:2560
	v_ldexp_f32 v1, v1, s5
	v_add_u32_e32 v7, 0x200, v76
	v_sub_u32_e32 v8, 0x7f, v16
	v_log_f32_e32 v1, v1
	v_ashrrev_i32_e32 v18, 4, v7
	v_cvt_f32_i32_e32 v7, v8
	v_cndmask_b32_e32 v6, 0, v193, vcc
	v_sub_f32_e32 v1, v1, v6
	v_add_u32_e32 v8, s0, v18
	v_mul_f32_e32 v6, v1, v7
	v_exp_f32_e32 v6, v6
	v_mad_i64_i32 v[14:15], s[28:29], v8, s84, v[10:11]
	s_movk_i32 s5, 0x88
	v_lshrrev_b32_e32 v26, 2, v66
	v_lshlrev_b32_e32 v28, 3, v66
	s_movk_i32 s16, 0x110
	v_lshlrev_b32_e32 v27, 2, v66
	v_and_b32_e32 v28, 24, v28
	v_and_b32_e32 v144, 48, v66
	s_waitcnt vmcnt(7)
	v_mov_b32_e32 v2, v198
	v_mov_b32_e32 v3, v199
	v_mov_b32_e32 v4, v200
	v_mov_b32_e32 v5, v201
	v_lshlrev_b32_e32 v7, 16, v2
	v_and_b32_e32 v2, 0xffff0000, v2
	v_lshlrev_b32_e32 v8, 16, v3
	v_and_b32_e32 v3, 0xffff0000, v3
	v_lshlrev_b32_e32 v9, 16, v4
	v_and_b32_e32 v4, 0xffff0000, v4
	v_lshlrev_b32_e32 v17, 16, v5
	v_and_b32_e32 v5, 0xffff0000, v5
	v_mul_f32_e32 v7, v6, v7
	v_mul_f32_e32 v2, v6, v2
	v_mul_f32_e32 v8, v6, v8
	v_mul_f32_e32 v3, v6, v3
	v_mul_f32_e32 v9, v6, v9
	v_mul_f32_e32 v4, v6, v4
	v_mul_f32_e32 v5, v6, v5
	v_mul_f32_e32 v17, v6, v17
	v_cvt_pk_bf16_f32 v2, v7, v2
	v_cvt_pk_bf16_f32 v3, v8, v3
	v_cvt_pk_bf16_f32 v4, v9, v4
	v_cvt_pk_bf16_f32 v5, v17, v5
	v_add_u32_e32 v17, 0x400, v76
	v_ashrrev_i32_e32 v20, 4, v17
	v_mad_u64_u32 v[16:17], s[28:29], v16, s5, v[0:1]
	v_sub_u32_e32 v17, 0x7f, v18
	v_cvt_f32_i32_e32 v19, v17
	v_lshl_add_u32 v22, v16, 1, 0
	v_add_u32_e32 v16, s0, v20
	ds_write_b128 v22, v[2:5] offset:17408
	v_mul_f32_e32 v19, v1, v19
	v_exp_f32_e32 v19, v19
	v_mad_i64_i32 v[16:17], s[28:29], v16, s84, v[10:11]
	s_waitcnt vmcnt(6)
	v_mov_b32_e32 v118, v202
	v_mov_b32_e32 v119, v203
	v_mov_b32_e32 v120, v204
	v_mov_b32_e32 v121, v205
	v_lshlrev_b32_e32 v2, 16, v118
	v_and_b32_e32 v3, 0xffff0000, v118
	v_lshlrev_b32_e32 v4, 16, v119
	v_and_b32_e32 v5, 0xffff0000, v119
	v_lshlrev_b32_e32 v6, 16, v120
	v_and_b32_e32 v7, 0xffff0000, v120
	v_lshlrev_b32_e32 v8, 16, v121
	v_and_b32_e32 v9, 0xffff0000, v121
	v_mul_f32_e32 v2, v19, v2
	v_mul_f32_e32 v3, v19, v3
	v_mul_f32_e32 v4, v19, v4
	v_mul_f32_e32 v5, v19, v5
	v_mul_f32_e32 v6, v19, v6
	v_mul_f32_e32 v7, v19, v7
	v_mul_f32_e32 v8, v19, v8
	v_mul_f32_e32 v9, v19, v9
	v_cvt_pk_bf16_f32 v2, v2, v3
	v_cvt_pk_bf16_f32 v3, v4, v5
	v_cvt_pk_bf16_f32 v4, v6, v7
	v_cvt_pk_bf16_f32 v5, v8, v9
	v_add_u32_e32 v19, 0x600, v76
	v_ashrrev_i32_e32 v23, 4, v19
	v_mad_u64_u32 v[18:19], s[28:29], v18, s5, v[0:1]
	v_sub_u32_e32 v19, 0x7f, v20
	v_cvt_f32_i32_e32 v21, v19
	v_lshl_add_u32 v24, v18, 1, 0
	v_add_u32_e32 v18, s0, v23
	v_mad_i64_i32 v[18:19], s[0:1], v18, s84, v[10:11]
	v_mul_f32_e32 v10, v1, v21
	v_exp_f32_e32 v10, v10
	ds_write_b128 v24, v[2:5] offset:17408
	s_waitcnt vmcnt(5)
	v_mov_b32_e32 v122, v206
	v_mov_b32_e32 v123, v207
	v_mov_b32_e32 v124, v208
	v_mov_b32_e32 v125, v209
	v_lshlrev_b32_e32 v2, 16, v122
	v_and_b32_e32 v3, 0xffff0000, v122
	v_lshlrev_b32_e32 v4, 16, v123
	v_and_b32_e32 v5, 0xffff0000, v123
	v_lshlrev_b32_e32 v6, 16, v124
	v_and_b32_e32 v7, 0xffff0000, v124
	v_lshlrev_b32_e32 v8, 16, v125
	v_and_b32_e32 v9, 0xffff0000, v125
	v_mul_f32_e32 v2, v10, v2
	v_mul_f32_e32 v3, v10, v3
	v_mul_f32_e32 v4, v10, v4
	v_mul_f32_e32 v5, v10, v5
	v_mul_f32_e32 v6, v10, v6
	v_mul_f32_e32 v7, v10, v7
	v_mul_f32_e32 v8, v10, v8
	v_mul_f32_e32 v9, v10, v9
	v_cvt_pk_bf16_f32 v2, v2, v3
	v_cvt_pk_bf16_f32 v3, v4, v5
	v_cvt_pk_bf16_f32 v4, v6, v7
	v_cvt_pk_bf16_f32 v5, v8, v9
	v_sub_u32_e32 v10, 0x7f, v23
	v_cvt_f32_i32_e32 v21, v10
	v_mad_u64_u32 v[10:11], s[0:1], v20, s5, v[0:1]
	v_lshl_add_u32 v25, v10, 1, 0
	v_mul_f32_e32 v1, v1, v21
	v_exp_f32_e32 v1, v1
	ds_write_b128 v25, v[2:5] offset:17408
	s_waitcnt vmcnt(4)
; #define LAS __attribute__((address_space(3)))
; __device__ __forceinline__ unsigned pk2(float lo, float hi) { return pg8::cvt_pk_bf16(lo, hi); }
; template <int NR, bool ZETA> __device__ __forceinline__ void ret_load_R(const bf16* Z, int r0, int c0, LAS unsigned char* dst, int tid, float lg2) {
;     ...
;     for (int it = 0; it < NR / 32; ++it) { const int ch = it * NTHR + tid, r = ch >> 4, c = ch & 15;
;         u32x4 v = *(const u32x4*)(Z + (size_t)(r0 + r) * IW + c0 + c * 8);
;         if (ZETA) { const float zs = __builtin_amdgcn_exp2f((float)(127 - r) * lg2); float f[8]; unpack8(v, f);
;             v.x = pk2(f[0] * zs, f[1] * zs); v.y = pk2(f[2] * zs, f[3] * zs); v.z = pk2(f[4] * zs, f[5] * zs); v.w = pk2(f[6] * zs, f[7] * zs); }
;         *(LAS u32x4*)(dst + (r * 136 + c * 8) * 2) = v; }
; __device__ __forceinline__ void ret_kv(const Args& a, int unit, LAS unsigned char* lds, int tid, int lane, int wave) {
;     ...
;     ret_load_R<128, true>(Z, r0, 768 + h * 128, lds + OFF_KS, tid, lg2);
;     ret_load_R<128, false>(Z, r0, 1280 + h * 128, lds + OFF_VT, tid, lg2);
;     __syncthreads();
	v_mov_b32_e32 v118, v210
	v_mov_b32_e32 v119, v211
	v_mov_b32_e32 v120, v212
	v_mov_b32_e32 v121, v213
	v_lshlrev_b32_e32 v2, 16, v118
	v_and_b32_e32 v3, 0xffff0000, v118
	v_lshlrev_b32_e32 v4, 16, v119
	v_and_b32_e32 v5, 0xffff0000, v119
	v_lshlrev_b32_e32 v6, 16, v120
	v_and_b32_e32 v7, 0xffff0000, v120
	v_lshlrev_b32_e32 v8, 16, v121
	v_and_b32_e32 v9, 0xffff0000, v121
	v_mul_f32_e32 v2, v1, v2
	v_mul_f32_e32 v3, v1, v3
	v_mul_f32_e32 v4, v1, v4
	v_mul_f32_e32 v5, v1, v5
	v_mul_f32_e32 v6, v1, v6
	v_mul_f32_e32 v7, v1, v7
	v_mul_f32_e32 v8, v1, v8
	v_mul_f32_e32 v1, v1, v9
	v_cvt_pk_bf16_f32 v2, v2, v3
	v_cvt_pk_bf16_f32 v3, v4, v5
	v_cvt_pk_bf16_f32 v4, v6, v7
	v_cvt_pk_bf16_f32 v5, v8, v1
	s_nop 0
	s_nop 0
	s_nop 0
	v_lshrrev_b32_e32 v1, 1, v76
	v_and_b32_e32 v29, 24, v1
	v_mad_u64_u32 v[0:1], s[0:1], v23, s5, v[0:1]
	v_and_or_b32 v56, v26, 3, v29
	s_lshl_b32 s1, s26, 5
	v_mad_u32_u24 v1, v56, s16, 0
	s_and_b32 s0, s1, 0x60
	v_add_u32_e32 v26, v1, v28
	s_and_b32 s5, s1, 0xffffff80
	s_or_b32 s1, s1, 0x60
	v_and_or_b32 v23, v27, 12, s0
	v_lshl_add_u32 v0, v0, 1, 0
	v_add_u32_e32 v57, s5, v26
	v_lshlrev_b32_e32 v58, 1, v23
	v_add_u32_e32 v59, s1, v26
	v_add_u32_e32 v48, v1, v58
	ds_write_b128 v0, v[2:5] offset:17408
	s_waitcnt vmcnt(3)
	v_mov_b32_e32 v6, v214
	v_mov_b32_e32 v7, v215
	v_mov_b32_e32 v8, v216
	v_mov_b32_e32 v9, v217
	ds_write_b128 v22, v[6:9] offset:52224
	s_waitcnt vmcnt(2)
	v_mov_b32_e32 v10, v218
	v_mov_b32_e32 v11, v219
	v_mov_b32_e32 v12, v220
	v_mov_b32_e32 v13, v221
	ds_write_b128 v24, v[10:13] offset:52224
	s_waitcnt vmcnt(1)
	v_mov_b32_e32 v14, v222
	v_mov_b32_e32 v15, v223
	v_mov_b32_e32 v16, v224
	v_mov_b32_e32 v17, v225
	ds_write_b128 v25, v[14:17] offset:52224
	s_waitcnt vmcnt(0)
	v_mov_b32_e32 v18, v226
	v_mov_b32_e32 v19, v227
	v_mov_b32_e32 v20, v228
	v_mov_b32_e32 v21, v229
	ds_write_b128 v0, v[18:21] offset:52224
	s_waitcnt lgkmcnt(0)
	s_barrier
; #define MFMA16(X, Y, ACC) ACC = __builtin_amdgcn_mfma_f32_16x16x32_bf16(X, Y, ACC, 0, 0, 0)
; __device__ __forceinline__ void ret_kv(const Args& a, int unit, LAS unsigned char* lds, int tid, int lane, int wave) {
;     ...
;     const int eb = (wave & 3) * 32, dh = (wave >> 2) * 64;
;     f32x4 acc[2][4];
; #pragma unroll
;     for (int i = 0; i < 2; ++i)
; #pragma unroll
;         for (int j = 0; j < 4; ++j) acc[i][j] = (f32x4){0.f, 0.f, 0.f, 0.f};
; #pragma unroll
;     for (int ks = 0; ks < 4; ++ks) {
;         bf16x8 vf[2], kf[4];
; #pragma unroll
;         for (int i = 0; i < 2; ++i) vf[i] = tr_frag(lds + OFF_VT, 272, 32 * ks, eb + i * 16, lane);
; #pragma unroll
;         for (int j = 0; j < 4; ++j) kf[j] = tr_frag(lds + OFF_KS, 272, 32 * ks, dh + j * 16, lane);
; #pragma unroll
;         for (int i = 0; i < 2; ++i)
; #pragma unroll
;             for (int j = 0; j < 4; ++j) MFMA16(kf[j], vf[i], acc[i][j]);
;         asm volatile("" ::: "memory");
;     }
;     float* KV = (float*)(a.ws + WS_KV) + (size_t)unit * 16384;
; #pragma unroll
;     for (int i = 0; i < 2; ++i)
; #pragma unroll
;         for (int j = 0; j < 4; ++j) *(f32x4*)(KV + (size_t)(eb + i * 16 + fr) * 128 + dh + j * 16 + 4 * fq) = acc[i][j];
;     __syncthreads();
	ds_read_b64_tr_b16 v[2:3], v57 offset:18496
	ds_read_b64_tr_b16 v[0:1], v57 offset:17408
	ds_read_b64_tr_b16 v[4:5], v57 offset:17440
	ds_read_b64_tr_b16 v[6:7], v57 offset:18528
	ds_read_b64_tr_b16 v[10:11], v48 offset:53312
	ds_read_b64_tr_b16 v[8:9], v48 offset:52224
	ds_read_b64_tr_b16 v[14:15], v48 offset:53344
	ds_read_b64_tr_b16 v[12:13], v48 offset:52256
	ds_read_b64_tr_b16 v[16:17], v57 offset:17472
	ds_read_b64_tr_b16 v[18:19], v57 offset:18560
	ds_read_b64_tr_b16 v[24:25], v59 offset:17408
	ds_read_b64_tr_b16 v[26:27], v59 offset:18496
	s_waitcnt lgkmcnt(6)
	v_mfma_f32_16x16x32_bf16 v[20:23], v[0:3], v[8:11], 0
	ds_read_b64_tr_b16 v[38:39], v57 offset:27200
	ds_read_b64_tr_b16 v[36:37], v57 offset:26112
	ds_read_b64_tr_b16 v[42:43], v48 offset:62016
	ds_read_b64_tr_b16 v[40:41], v48 offset:60928
	ds_read_b64_tr_b16 v[44:45], v57 offset:26144
	ds_read_b64_tr_b16 v[46:47], v57 offset:27232
	v_add_u32_e32 v60, s18, v58
	v_mfma_f32_16x16x32_bf16 v[28:31], v[4:7], v[8:11], 0
	s_lshl_b32 s1, s26, 4
	s_ashr_i32 s5, s4, 31
	s_and_b32 s28, s1, 0xffffffc0
	s_waitcnt lgkmcnt(8)
	v_mfma_f32_16x16x32_bf16 v[32:35], v[16:19], v[8:11], 0
	s_lshl_b64 s[4:5], s[4:5], 16
	s_waitcnt lgkmcnt(6)
	v_mfma_f32_16x16x32_bf16 v[8:11], v[24:27], v[8:11], 0
	v_mfma_f32_16x16x32_bf16 v[0:3], v[0:3], v[12:15], 0
	v_mfma_f32_16x16x32_bf16 v[4:7], v[4:7], v[12:15], 0
	v_mfma_f32_16x16x32_bf16 v[16:19], v[16:19], v[12:15], 0
	v_mfma_f32_16x16x32_bf16 v[12:15], v[24:27], v[12:15], 0
	ds_read_b64_tr_b16 v[26:27], v48 offset:62048
	ds_read_b64_tr_b16 v[24:25], v48 offset:60960
	ds_read_b64_tr_b16 v[48:49], v57 offset:26176
	ds_read_b64_tr_b16 v[50:51], v57 offset:27264
	ds_read_b64_tr_b16 v[52:53], v59 offset:26112
	ds_read_b64_tr_b16 v[54:55], v59 offset:27200
	s_waitcnt lgkmcnt(8)
	v_mfma_f32_16x16x32_bf16 v[20:23], v[36:39], v[40:43], v[20:23]
	s_waitcnt lgkmcnt(6)
	v_mfma_f32_16x16x32_bf16 v[28:31], v[44:47], v[40:43], v[28:31]
	s_waitcnt lgkmcnt(2)
	v_mfma_f32_16x16x32_bf16 v[32:35], v[48:51], v[40:43], v[32:35]
	s_waitcnt lgkmcnt(0)
	v_mfma_f32_16x16x32_bf16 v[8:11], v[52:55], v[40:43], v[8:11]
	v_mov_b32_e32 v40, 0x4400
	v_mad_u32_u24 v40, v56, s16, v40
	v_add3_u32 v61, s18, v40, v58
	v_mfma_f32_16x16x32_bf16 v[0:3], v[36:39], v[24:27], v[0:3]
	v_add_u32_e32 v42, v60, v40
	ds_read_b64_tr_b16 v[38:39], v57 offset:35904
	ds_read_b64_tr_b16 v[36:37], v57 offset:34816
	v_mfma_f32_16x16x32_bf16 v[4:7], v[44:47], v[24:27], v[4:7]
	ds_read_b64_tr_b16 v[40:41], v42
	ds_read_b64_tr_b16 v[42:43], v42 offset:1088
	ds_read_b64_tr_b16 v[44:45], v57 offset:34848
	ds_read_b64_tr_b16 v[46:47], v57 offset:35936
	v_mfma_f32_16x16x32_bf16 v[16:19], v[48:51], v[24:27], v[16:19]
	v_mfma_f32_16x16x32_bf16 v[12:15], v[52:55], v[24:27], v[12:15]
	ds_read_b64_tr_b16 v[24:25], v61 offset:32
	ds_read_b64_tr_b16 v[26:27], v61 offset:1120
	ds_read_b64_tr_b16 v[48:49], v57 offset:34880
	ds_read_b64_tr_b16 v[50:51], v57 offset:35968
	ds_read_b64_tr_b16 v[52:53], v59 offset:34816
	ds_read_b64_tr_b16 v[54:55], v59 offset:35904
	s_waitcnt lgkmcnt(8)
	v_mfma_f32_16x16x32_bf16 v[20:23], v[36:39], v[40:43], v[20:23]
	s_waitcnt lgkmcnt(4)
	v_mfma_f32_16x16x32_bf16 v[0:3], v[36:39], v[24:27], v[0:3]
	v_mov_b32_e32 v36, 0x6600
	v_mad_u32_u24 v36, v56, s16, v36
	v_readlane_b32 s16, v252, 48
	v_mfma_f32_16x16x32_bf16 v[28:31], v[44:47], v[40:43], v[28:31]
	v_readlane_b32 s17, v252, 49
	s_add_u32 s4, s16, s4
	s_addc_u32 s5, s17, s5
	v_mfma_f32_16x16x32_bf16 v[4:7], v[44:47], v[24:27], v[4:7]
	v_add3_u32 v46, s18, v36, v58
	v_add_u32_e32 v44, v60, v36
	s_ashr_i32 s29, s28, 31
	s_waitcnt lgkmcnt(2)
	v_mfma_f32_16x16x32_bf16 v[32:35], v[48:51], v[40:43], v[32:35]
	v_and_or_b32 v56, v76, 15, s0
	s_lshl_b64 s[0:1], s[28:29], 2
	s_add_u32 s0, s4, s0
	s_waitcnt lgkmcnt(0)
	v_mfma_f32_16x16x32_bf16 v[8:11], v[52:55], v[40:43], v[8:11]
	ds_read_b64_tr_b16 v[38:39], v57 offset:44608
	ds_read_b64_tr_b16 v[36:37], v57 offset:43520
	ds_read_b64_tr_b16 v[40:41], v57 offset:43552
	ds_read_b64_tr_b16 v[42:43], v57 offset:44640
	s_addc_u32 s1, s5, s1
	v_mfma_f32_16x16x32_bf16 v[16:19], v[48:51], v[24:27], v[16:19]
	v_mfma_f32_16x16x32_bf16 v[12:15], v[52:55], v[24:27], v[12:15]
	ds_read_b64_tr_b16 v[24:25], v44
	ds_read_b64_tr_b16 v[26:27], v44 offset:1088
	ds_read_b64_tr_b16 v[44:45], v46 offset:32
	ds_read_b64_tr_b16 v[46:47], v46 offset:1120
	ds_read_b64_tr_b16 v[48:49], v57 offset:43584
	ds_read_b64_tr_b16 v[50:51], v57 offset:44672
	ds_read_b64_tr_b16 v[52:53], v59 offset:43520
	ds_read_b64_tr_b16 v[54:55], v59 offset:44608
	s_waitcnt lgkmcnt(6)
	v_mfma_f32_16x16x32_bf16 v[20:23], v[36:39], v[24:27], v[20:23]
	v_mfma_f32_16x16x32_bf16 v[28:31], v[40:43], v[24:27], v[28:31]
	s_waitcnt lgkmcnt(2)
	v_mfma_f32_16x16x32_bf16 v[32:35], v[48:51], v[24:27], v[32:35]
	s_waitcnt lgkmcnt(0)
	v_mfma_f32_16x16x32_bf16 v[8:11], v[52:55], v[24:27], v[8:11]
	v_lshl_add_u64 v[24:25], s[0:1], 0, v[144:145]
	v_lshlrev_b32_e32 v144, 9, v56
	v_lshl_add_u64 v[24:25], v[24:25], 0, v[144:145]
	v_add_co_u32_e32 v26, vcc, 0x2000, v24
	v_mfma_f32_16x16x32_bf16 v[0:3], v[36:39], v[44:47], v[0:3]
	s_nop 0
	v_addc_co_u32_e32 v27, vcc, 0, v25, vcc
	s_mov_b64 s[0:1], 0
	v_mfma_f32_16x16x32_bf16 v[4:7], v[40:43], v[44:47], v[4:7]
	v_mfma_f32_16x16x32_bf16 v[16:19], v[48:51], v[44:47], v[16:19]
	v_mfma_f32_16x16x32_bf16 v[12:15], v[52:55], v[44:47], v[12:15]
	global_store_dwordx4 v[24:25], v[20:23], off
	global_store_dwordx4 v[24:25], v[28:31], off offset:64
	global_store_dwordx4 v[24:25], v[32:35], off offset:128
	global_store_dwordx4 v[24:25], v[8:11], off offset:192
	global_store_dwordx4 v[26:27], v[0:3], off
	s_nop 0
	global_store_dwordx4 v[26:27], v[4:7], off offset:64
	global_store_dwordx4 v[26:27], v[16:19], off offset:128
	global_store_dwordx4 v[26:27], v[12:15], off offset:192
	s_barrier
